# baseline (speedup 1.0000x reference)
.LBB0_122:
	s_mov_b64 s[4:5], -1
	s_and_b64 vcc, exec, s[84:85]
	s_barrier
	s_cbranch_vccz .LBB0_171
	s_mov_b32 s4, -1
	s_sub_i32 s20, 0, s11
	v_mbcnt_lo_u32_b32 v0, s4, 0
	v_mbcnt_hi_u32_b32 v0, s4, v0
	v_readlane_b32 s4, v255, 0
	v_mov_b32_e32 v114, v112
	v_mov_b32_e32 v115, v112
	v_or_b32_e32 v40, s4, v0
	s_movk_i32 s4, 0xffe0
	v_ashrrev_i32_e32 v41, 1, v40
	v_bfi_b32 v0, s4, v41, v40
	s_lshl_b64 s[4:5], s[20:21], 15
	v_ashrrev_i32_e32 v1, 31, v0
	s_add_u32 s6, s94, s4
	v_bfe_u32 v193, v40, 5, 1
	v_lshlrev_b64 v[0:1], 11, v[0:1]
	s_addc_u32 s7, s95, s5
	v_lshl_add_u64 v[0:1], s[98:99], 0, v[0:1]
	v_lshlrev_b32_e32 v162, 5, v193
	s_add_u32 s4, s96, s4
	v_lshl_add_u64 v[0:1], v[0:1], 0, v[162:163]
	v_lshlrev_b32_e32 v166, 4, v40
	s_addc_u32 s5, s97, s5
	global_load_dwordx4 v[126:129], v[0:1], off offset:16 nt
	global_load_dwordx4 v[122:125], v[0:1], off nt
	global_load_dwordx4 v[134:137], v[0:1], off offset:80 nt
	global_load_dwordx4 v[130:133], v[0:1], off offset:64 nt
	v_ashrrev_i32_e32 v2, 3, v40
	v_and_b32_e32 v0, 0x70, v166
	v_mov_b32_e32 v116, v112
	v_mov_b32_e32 v117, v112
	v_mov_b32_e32 v118, v112
	v_mov_b32_e32 v119, v112
	s_cmp_gt_i32 s11, 0
	v_lshl_or_b32 v168, v2, 9, v0
	v_mov_b32_e32 v113, v112
	v_mov_b64_e32 v[120:121], v[118:119]
	s_cselect_b32 s5, s93, s5
	s_cselect_b32 s4, s92, s4
	v_ashrrev_i32_e32 v167, 31, v166
	v_mov_b64_e32 v[118:119], v[116:117]
	v_mov_b64_e32 v[116:117], v[114:115]
	v_mov_b64_e32 v[114:115], v[112:113]
	v_lshrrev_b32_e32 v44, 1, v40
	v_xor_b32_e32 v44, v44, v40
	v_and_b32_e32 v44, 8, v44
	v_cmp_eq_u32_e32 vcc, 0, v44
	s_nop 1
	v_cndmask_b32_e32 v114, 0, v112, vcc
	v_mov_b32_e32 v115, v114
	v_mov_b32_e32 v116, v114
	v_mov_b32_e32 v117, v114
	v_mov_b32_e32 v118, v114
	v_mov_b32_e32 v119, v114
	v_mov_b32_e32 v120, v114
	v_mov_b32_e32 v121, v114
	s_cselect_b32 s7, s91, s7
	s_cselect_b32 s6, s90, s6
	v_lshl_add_u64 v[0:1], s[4:5], 0, v[166:167]
	v_ashrrev_i32_e32 v169, 31, v168
	global_load_dwordx4 v[146:149], v[0:1], off
	v_lshl_add_u64 v[0:1], s[6:7], 0, v[168:169]
	global_load_dwordx4 v[150:153], v[0:1], off
	v_and_b32_e32 v113, 31, v40
	v_lshlrev_b32_e32 v42, 1, v193
	v_and_b32_e32 v0, 7, v41
	v_lshlrev_b32_e32 v1, 7, v2
	v_lshrrev_b32_e32 v2, 1, v2
	v_xor_b32_e32 v2, v2, v40
	v_lshlrev_b32_e32 v165, 7, v113
	v_bitop3_b32 v4, v42, v41, 7 bitop3:0x78
	v_lshlrev_b32_e32 v2, 4, v2
	v_add_u32_e32 v5, 0, v165
	v_bitop3_b32 v6, v42, v0, 1 bitop3:0x36
	v_bitop3_b32 v7, v42, v0, 4 bitop3:0x36
	v_bitop3_b32 v0, v42, v0, 5 bitop3:0x36
	s_movk_i32 s4, 0x70
	v_lshlrev_b32_e32 v197, 4, v4
	v_add_u32_e32 v3, 0, v166
	v_and_or_b32 v1, v2, s4, v1
	v_lshlrev_b32_e32 v196, 4, v6
	v_lshlrev_b32_e32 v195, 4, v7
	v_lshlrev_b32_e32 v194, 4, v0
	v_add_u32_e32 v202, v5, v197
	v_add_u32_e32 v201, 0, v1
	v_add_u32_e32 v203, v5, v196
	v_add_u32_e32 v204, v5, v195
	v_add_u32_e32 v205, v5, v194
	s_waitcnt vmcnt(0)
	s_waitcnt vmcnt(1)
	ds_write_b128 v3, v[146:149]
	s_waitcnt vmcnt(0)
	ds_write_b128 v201, v[150:153] offset:32768
	s_waitcnt lgkmcnt(0)
	s_barrier
	ds_read_b128 v[0:3], v202 offset:32768
	ds_read_b128 v[32:35], v202 offset:36864
	ds_read_b128 v[4:7], v203 offset:32768
	ds_read_b128 v[36:39], v203 offset:36864
	ds_read_b128 v[44:47], v204 offset:32768
	ds_read_b128 v[52:55], v204 offset:36864
	ds_read_b128 v[48:51], v205 offset:32768
	ds_read_b128 v[56:59], v205 offset:36864
	s_waitcnt lgkmcnt(5)
	v_mfma_f32_32x32x64_f8f6f4 v[16:31], v[0:7], v[122:129], 0
	s_waitcnt lgkmcnt(4)
	v_mfma_f32_32x32x64_f8f6f4 v[0:15], v[32:39], v[122:129], 0
	s_waitcnt lgkmcnt(1)
	v_mfma_f32_32x32x64_f8f6f4 v[16:31], v[44:51], v[130:137], v[16:31]
	s_waitcnt lgkmcnt(0)
	v_mfma_f32_32x32x64_f8f6f4 v[0:15], v[52:59], v[130:137], v[0:15]
	s_nop 15
	s_nop 7
	v_max_f32_e32 v32, v17, v17
	v_max_f32_e32 v33, v16, v16
	v_max_f32_e32 v32, v33, v32
	v_max3_f32 v32, v32, v18, v19
	v_max3_f32 v32, v32, v20, v21
	v_max3_f32 v32, v32, v22, v23
	v_max3_f32 v32, v32, v24, v25
	v_max3_f32 v32, v32, v26, v27
	v_max3_f32 v32, v32, v28, v29
	v_max3_f32 v32, v32, v30, v31
	v_max3_f32 v32, v32, v0, v1
	v_max3_f32 v32, v32, v2, v3
	v_max3_f32 v32, v32, v4, v5
	v_max3_f32 v32, v32, v6, v7
	v_max3_f32 v32, v32, v8, v9
	v_max3_f32 v32, v32, v10, v11
	v_max3_f32 v32, v32, v12, v13
	v_max3_f32 v32, v32, v14, v15
	v_mov_b32_e32 v33, v32
	s_nop 1
	v_permlane32_swap_b32_e32 v32, v33
	v_max_f32_e32 v33, v33, v33
	v_max_f32_e32 v32, v32, v32
	v_max_f32_e32 v32, v32, v33
	v_add_f32_e32 v33, 0x7149f2ca, v32
	v_cmp_ge_f32_e32 vcc, s63, v33
	s_cmp_eq_u64 vcc, exec
	s_cbranch_scc0 .LBB0_234
	v_mov_b32_e32 v217, 1.0
	v_mov_b32_e32 v138, 0
	v_mov_b32_e32 v172, 0xf149f2ca
	s_cmp_lt_i32 s11, 2
	s_mov_b64 s[8:9], -1
	s_cbranch_scc0 .LBB0_126

.LBB0_138:
	ds_read_b128 v[80:83], v213 offset:49152
	ds_read_b128 v[84:87], v214 offset:49152
	ds_read_b128 v[222:225], v202 offset:53248
	ds_read_b128 v[226:229], v203 offset:53248
	ds_read_b128 v[230:233], v215 offset:49152
	ds_read_b128 v[234:237], v216 offset:49152
	ds_read_b128 v[238:241], v204 offset:53248
	ds_read_b128 v[242:245], v205 offset:53248
	s_waitcnt lgkmcnt(6)
	v_mfma_f32_32x32x64_f8f6f4 v[96:111], v[80:87], v[122:129], 0
	s_waitcnt lgkmcnt(4)
	v_mfma_f32_32x32x64_f8f6f4 v[80:95], v[222:229], v[122:129], 0
	s_waitcnt lgkmcnt(2)
	v_mfma_f32_32x32x64_f8f6f4 v[96:111], v[230:237], v[130:137], v[96:111]
	s_waitcnt lgkmcnt(0)
	v_mfma_f32_32x32x64_f8f6f4 v[80:95], v[238:245], v[130:137], v[80:95]
	v_exp_f32_e32 v139, v170
	v_exp_f32_e32 v162, v171
	v_exp_f32_e32 v158, v158
	v_exp_f32_e32 v159, v159
	v_exp_f32_e32 v154, v154
	v_exp_f32_e32 v155, v155
	v_exp_f32_e32 v142, v142
	v_exp_f32_e32 v143, v143
	v_exp_f32_e32 v160, v160
	v_exp_f32_e32 v161, v161
	v_exp_f32_e32 v156, v156
	v_exp_f32_e32 v157, v157
	v_exp_f32_e32 v144, v144
	v_exp_f32_e32 v145, v145
	v_exp_f32_e32 v140, v140
	v_exp_f32_e32 v141, v141
	v_cvt_pk_fp8_f32 v222, v219, v220
	v_cvt_pk_fp8_f32 v226, v139, v162
	v_cvt_pk_fp8_f32 v223, v185, v218
	v_cvt_pk_fp8_f32 v227, v158, v159
	v_cvt_pk_fp8_f32 v224, v180, v182
	v_cvt_pk_fp8_f32 v228, v154, v155
	v_cvt_pk_fp8_f32 v225, v177, v178
	v_cvt_pk_fp8_f32 v229, v142, v143
	v_cvt_pk_fp8_f32 v222, v179, v181 op_sel:[0,0,1]
	v_cvt_pk_fp8_f32 v226, v160, v161 op_sel:[0,0,1]
	v_cvt_pk_fp8_f32 v223, v183, v184 op_sel:[0,0,1]
	v_cvt_pk_fp8_f32 v227, v156, v157 op_sel:[0,0,1]
	v_cvt_pk_fp8_f32 v224, v173, v174 op_sel:[0,0,1]
	v_cvt_pk_fp8_f32 v228, v144, v145 op_sel:[0,0,1]
	v_cvt_pk_fp8_f32 v225, v175, v176 op_sel:[0,0,1]
	v_cvt_pk_fp8_f32 v229, v140, v141 op_sel:[0,0,1]
	s_add_i32 s4, s13, -1
	s_cmp_lt_i32 s4, s11
	s_cselect_b32 s5, 0, s11
	s_cselect_b32 s9, s91, s95
	s_cselect_b32 s8, s90, s94
	s_cselect_b32 s14, s92, s96
	s_cselect_b32 s15, s93, s97
	s_sub_i32 s20, s4, s5
	s_lshl_b64 s[4:5], s[20:21], 15
	s_add_u32 s8, s8, s4
	s_addc_u32 s9, s9, s5
	s_add_u32 s4, s14, s4
	s_addc_u32 s5, s15, s5
	v_lshl_add_u64 v[140:141], s[4:5], 0, v[166:167]
	global_load_dwordx4 v[158:161], v[140:141], off
	v_lshl_add_u64 v[140:141], s[8:9], 0, v[168:169]
	global_load_dwordx4 v[154:157], v[140:141], off
	v_add_u32_e32 v162, v210, v199
	v_add_u32_e32 v218, v210, v200
	ds_read_b128 v[174:177], v162
	ds_read_b128 v[230:233], v162 offset:2048
	ds_read_b128 v[178:181], v218
	ds_read_b128 v[234:237], v218 offset:2048
	ds_read_b128 v[238:241], v162 offset:4096
	ds_read_b128 v[246:249], v162 offset:6144
	ds_read_b128 v[242:245], v218 offset:4096
	ds_read_b128 v[250:253], v218 offset:6144
	s_waitcnt lgkmcnt(5)
	v_mfma_f32_32x32x64_f8f6f4 v[48:63], v[222:229], v[174:181], v[48:63]
	s_waitcnt lgkmcnt(4)
	v_mfma_f32_32x32x64_f8f6f4 v[32:47], v[222:229], v[230:237], v[32:47]
	s_waitcnt lgkmcnt(1)
	v_mfma_f32_32x32x64_f8f6f4 v[16:31], v[222:229], v[238:245], v[16:31]
	s_waitcnt lgkmcnt(0)
	v_mfma_f32_32x32x64_f8f6f4 v[0:15], v[222:229], v[246:253], v[0:15]
	v_mfma_f32_16x16x128_f8f6f4 v[64:67], v[222:229], v[114:121], v[64:67]
	v_max_f32_e32 v139, v97, v97
	v_max_f32_e32 v140, v96, v96
	v_max_f32_e32 v139, v140, v139
	v_max3_f32 v139, v139, v98, v99
	v_max3_f32 v139, v139, v100, v101
	v_max3_f32 v139, v139, v102, v103
	v_max3_f32 v139, v139, v104, v105
	v_max3_f32 v139, v139, v106, v107
	v_max3_f32 v139, v139, v108, v109
	v_max3_f32 v139, v139, v110, v111
	v_max3_f32 v139, v139, v80, v81
	v_max3_f32 v139, v139, v82, v83
	v_max3_f32 v139, v139, v84, v85
	v_max3_f32 v139, v139, v86, v87
	v_max3_f32 v139, v139, v88, v89
	v_max3_f32 v139, v139, v90, v91
	v_max3_f32 v139, v139, v92, v93
	v_max3_f32 v139, v139, v94, v95
	v_mov_b32_e32 v140, v139
	s_nop 1
	v_permlane32_swap_b32_e32 v139, v140
	v_max_f32_e32 v140, v140, v140
	v_max_f32_e32 v139, v139, v139
	v_max_f32_e32 v139, v139, v140
	v_sub_f32_e32 v140, v139, v172
	v_cmp_ge_f32_e32 vcc, s63, v140
	s_cmp_lg_u64 vcc, exec
	s_cselect_b64 s[8:9], -1, 0
	s_mov_b64 vcc, s[8:9]
	s_cbranch_vccnz .LBB0_156
	v_mov_b32_e32 v140, v138

.LBB0_141:
	s_barrier
	s_waitcnt vmcnt(2)
	s_andn2_b64 vcc, exec, s[8:9]
	ds_write_b128 v208, v[146:149]
	ds_write_b128 v201, v[150:153] offset:32768
	s_cbranch_vccnz .LBB0_145
	s_and_saveexec_b64 s[4:5], s[6:7]
	ds_write_b32 v211, v209 offset:128
	s_or_b64 exec, exec, s[4:5]
	s_waitcnt lgkmcnt(0)
	v_add_u32_e32 v138, v198, v212
	ds_read_b128 v[142:145], v138 offset:224
	ds_read_b128 v[170:173], v138 offset:192
	ds_read_b128 v[174:177], v138 offset:160
	ds_read_b128 v[178:181], v138 offset:128
	s_waitcnt lgkmcnt(3)
	v_pk_mul_f32 v[60:61], v[60:61], v[142:143]
	s_waitcnt lgkmcnt(2)
	v_pk_mul_f32 v[56:57], v[56:57], v[170:171]
	s_waitcnt lgkmcnt(1)
	v_pk_mul_f32 v[52:53], v[52:53], v[174:175]
	v_pk_mul_f32 v[62:63], v[62:63], v[144:145]
	v_pk_mul_f32 v[58:59], v[58:59], v[172:173]
	v_pk_mul_f32 v[54:55], v[54:55], v[176:177]
	s_waitcnt lgkmcnt(0)
	v_pk_mul_f32 v[50:51], v[50:51], v[180:181]
	v_pk_mul_f32 v[48:49], v[48:49], v[178:179]
	v_pk_mul_f32 v[44:45], v[44:45], v[142:143]
	v_pk_mul_f32 v[40:41], v[40:41], v[170:171]
	v_pk_mul_f32 v[36:37], v[36:37], v[174:175]
	v_pk_mul_f32 v[46:47], v[46:47], v[144:145]
	v_pk_mul_f32 v[42:43], v[42:43], v[172:173]
	v_pk_mul_f32 v[38:39], v[38:39], v[176:177]
	v_pk_mul_f32 v[34:35], v[34:35], v[180:181]
	v_pk_mul_f32 v[32:33], v[32:33], v[178:179]
	v_pk_mul_f32 v[28:29], v[28:29], v[142:143]
	v_pk_mul_f32 v[24:25], v[24:25], v[170:171]
	v_pk_mul_f32 v[20:21], v[20:21], v[174:175]
	v_pk_mul_f32 v[30:31], v[30:31], v[144:145]
	v_pk_mul_f32 v[26:27], v[26:27], v[172:173]
	v_pk_mul_f32 v[22:23], v[22:23], v[176:177]
	v_pk_mul_f32 v[18:19], v[18:19], v[180:181]
	v_pk_mul_f32 v[16:17], v[16:17], v[178:179]
	v_pk_mul_f32 v[12:13], v[12:13], v[142:143]
	v_pk_mul_f32 v[8:9], v[8:9], v[170:171]
	v_pk_mul_f32 v[4:5], v[4:5], v[174:175]
	v_pk_mul_f32 v[14:15], v[14:15], v[144:145]
	v_pk_mul_f32 v[10:11], v[10:11], v[172:173]
	v_pk_mul_f32 v[6:7], v[6:7], v[176:177]
	v_pk_mul_f32 v[2:3], v[2:3], v[180:181]
	v_pk_mul_f32 v[0:1], v[0:1], v[178:179]
	v_mbcnt_lo_u32_b32 v138, -1, 0
	v_mbcnt_hi_u32_b32 v138, -1, v138
	v_and_b32_e32 v142, 8, v138
	v_and_b32_e32 v138, 0x30, v138
	v_lshl_add_u32 v138, v142, 3, v138
	v_add_u32_e32 v138, v138, v198
	ds_read_b128 v[142:145], v138 offset:128
	s_waitcnt lgkmcnt(0)
	v_pk_mul_f32 v[64:65], v[64:65], v[142:143]
	v_pk_mul_f32 v[66:67], v[66:67], v[144:145]

.LBB0_147:
	v_exp_f32_e32 v170, v170
	v_exp_f32_e32 v171, v171
	v_exp_f32_e32 v174, v174
	v_exp_f32_e32 v175, v175
	v_exp_f32_e32 v178, v178
	v_exp_f32_e32 v179, v179
	v_exp_f32_e32 v182, v182
	v_exp_f32_e32 v183, v183
	v_cvt_pk_fp8_f32 v138, v235, v236
	v_exp_f32_e32 v172, v172
	v_exp_f32_e32 v173, v173
	v_exp_f32_e32 v176, v176
	v_exp_f32_e32 v177, v177
	v_exp_f32_e32 v184, v184
	v_exp_f32_e32 v185, v185
	v_exp_f32_e32 v180, v180
	v_exp_f32_e32 v181, v181
	v_cvt_pk_fp8_f32 v142, v170, v171
	v_cvt_pk_fp8_f32 v139, v233, v234
	v_cvt_pk_fp8_f32 v143, v174, v175
	v_cvt_pk_fp8_f32 v138, v227, v229 op_sel:[0,0,1]
	v_cvt_pk_fp8_f32 v140, v228, v230
	v_cvt_pk_fp8_f32 v144, v178, v179
	v_cvt_pk_fp8_f32 v141, v225, v226
	v_cvt_pk_fp8_f32 v145, v182, v183
	v_cvt_pk_fp8_f32 v142, v172, v173 op_sel:[0,0,1]
	v_cvt_pk_fp8_f32 v139, v231, v232 op_sel:[0,0,1]
	v_cvt_pk_fp8_f32 v143, v176, v177 op_sel:[0,0,1]
	v_cvt_pk_fp8_f32 v140, v221, v222 op_sel:[0,0,1]
	v_cvt_pk_fp8_f32 v144, v184, v185 op_sel:[0,0,1]
	v_cvt_pk_fp8_f32 v141, v223, v224 op_sel:[0,0,1]
	v_cvt_pk_fp8_f32 v145, v180, v181 op_sel:[0,0,1]
	ds_read_b128 v[170:173], v162 offset:16384
	ds_read_b128 v[178:181], v162 offset:18432
	ds_read_b128 v[174:177], v218 offset:16384
	ds_read_b128 v[182:185], v218 offset:18432
	ds_read_b128 v[222:225], v162 offset:20480
	ds_read_b128 v[230:233], v162 offset:22528
	ds_read_b128 v[226:229], v218 offset:20480
	ds_read_b128 v[234:237], v218 offset:22528
	s_waitcnt lgkmcnt(5)
	v_mfma_f32_32x32x64_f8f6f4 v[48:63], v[138:145], v[170:177], v[48:63]
	s_waitcnt lgkmcnt(4)
	v_mfma_f32_32x32x64_f8f6f4 v[32:47], v[138:145], v[178:185], v[32:47]
	s_waitcnt lgkmcnt(1)
	v_mfma_f32_32x32x64_f8f6f4 v[16:31], v[138:145], v[222:229], v[16:31]
	s_waitcnt lgkmcnt(0)
	v_mfma_f32_32x32x64_f8f6f4 v[0:15], v[138:145], v[230:237], v[0:15]
	v_mfma_f32_16x16x128_f8f6f4 v[64:67], v[138:145], v[114:121], v[64:67]
	v_max_f32_e32 v138, v97, v97
	v_max_f32_e32 v139, v96, v96
	v_max_f32_e32 v138, v139, v138
	v_max3_f32 v138, v138, v98, v99
	v_max3_f32 v138, v138, v100, v101
	v_max3_f32 v138, v138, v102, v103
	v_max3_f32 v138, v138, v104, v105
	v_max3_f32 v138, v138, v106, v107
	v_max3_f32 v138, v138, v108, v109
	v_max3_f32 v138, v138, v110, v111
	v_max3_f32 v138, v138, v80, v81
	v_max3_f32 v138, v138, v82, v83
	v_max3_f32 v138, v138, v84, v85
	v_max3_f32 v138, v138, v86, v87
	v_max3_f32 v138, v138, v88, v89
	v_max3_f32 v138, v138, v90, v91
	v_max3_f32 v138, v138, v92, v93
	v_max3_f32 v138, v138, v94, v95
	v_mov_b32_e32 v139, v138
	s_nop 1
	v_permlane32_swap_b32_e32 v138, v139
	v_max_f32_e32 v139, v139, v139
	v_max_f32_e32 v138, v138, v138
	v_max_f32_e32 v138, v138, v139
	v_sub_f32_e32 v139, v138, v219
	v_cmp_ge_f32_e32 vcc, s63, v139
	s_cmp_lg_u64 vcc, exec
	s_cselect_b64 s[8:9], -1, 0
	s_mov_b64 vcc, s[8:9]
	s_cbranch_vccnz .LBB0_157
	v_mov_b32_e32 v162, v220

.LBB0_150:
	s_barrier
	s_waitcnt vmcnt(2)
	s_andn2_b64 vcc, exec, s[8:9]
	s_waitcnt vmcnt(1)
	ds_write_b128 v208, v[158:161] offset:16384
	s_waitcnt vmcnt(0)
	ds_write_b128 v201, v[154:157] offset:49152
	s_cbranch_vccnz .LBB0_154
	s_and_saveexec_b64 s[8:9], s[6:7]
	ds_write_b32 v211, v139 offset:128
	s_or_b64 exec, exec, s[8:9]
	s_waitcnt lgkmcnt(0)
	v_add_u32_e32 v144, v198, v212
	ds_read_b128 v[140:143], v144 offset:224
	ds_read_b128 v[154:157], v144 offset:192
	ds_read_b128 v[158:161], v144 offset:128
	ds_read_b128 v[174:177], v144 offset:160
	s_waitcnt lgkmcnt(3)
	v_pk_mul_f32 v[62:63], v[62:63], v[142:143]
	v_pk_mul_f32 v[60:61], v[60:61], v[140:141]
	s_waitcnt lgkmcnt(2)
	v_pk_mul_f32 v[58:59], v[58:59], v[156:157]
	v_pk_mul_f32 v[56:57], v[56:57], v[154:155]
	s_waitcnt lgkmcnt(0)
	v_pk_mul_f32 v[54:55], v[54:55], v[176:177]
	v_pk_mul_f32 v[52:53], v[52:53], v[174:175]
	v_pk_mul_f32 v[50:51], v[50:51], v[160:161]
	v_pk_mul_f32 v[48:49], v[48:49], v[158:159]
	v_pk_mul_f32 v[46:47], v[46:47], v[142:143]
	v_pk_mul_f32 v[44:45], v[44:45], v[140:141]
	v_pk_mul_f32 v[42:43], v[42:43], v[156:157]
	v_pk_mul_f32 v[40:41], v[40:41], v[154:155]
	v_pk_mul_f32 v[38:39], v[38:39], v[176:177]
	v_pk_mul_f32 v[36:37], v[36:37], v[174:175]
	v_pk_mul_f32 v[34:35], v[34:35], v[160:161]
	v_pk_mul_f32 v[32:33], v[32:33], v[158:159]
	v_pk_mul_f32 v[30:31], v[30:31], v[142:143]
	v_pk_mul_f32 v[28:29], v[28:29], v[140:141]
	v_pk_mul_f32 v[26:27], v[26:27], v[156:157]
	v_pk_mul_f32 v[24:25], v[24:25], v[154:155]
	v_pk_mul_f32 v[22:23], v[22:23], v[176:177]
	v_pk_mul_f32 v[20:21], v[20:21], v[174:175]
	v_pk_mul_f32 v[18:19], v[18:19], v[160:161]
	v_pk_mul_f32 v[16:17], v[16:17], v[158:159]
	v_pk_mul_f32 v[14:15], v[14:15], v[142:143]
	v_pk_mul_f32 v[12:13], v[12:13], v[140:141]
	v_pk_mul_f32 v[10:11], v[10:11], v[156:157]
	v_pk_mul_f32 v[8:9], v[8:9], v[154:155]
	v_pk_mul_f32 v[6:7], v[6:7], v[176:177]
	v_pk_mul_f32 v[4:5], v[4:5], v[174:175]
	v_pk_mul_f32 v[2:3], v[2:3], v[160:161]
	v_pk_mul_f32 v[0:1], v[0:1], v[158:159]
	v_mbcnt_lo_u32_b32 v144, -1, 0
	v_mbcnt_hi_u32_b32 v144, -1, v144
	v_and_b32_e32 v140, 8, v144
	v_and_b32_e32 v144, 0x30, v144
	v_lshl_add_u32 v144, v140, 3, v144
	v_add_u32_e32 v144, v144, v198
	ds_read_b128 v[140:143], v144 offset:128
	s_waitcnt lgkmcnt(0)
	v_pk_mul_f32 v[64:65], v[64:65], v[140:141]
	v_pk_mul_f32 v[66:67], v[66:67], v[142:143]

.LBB0_160:
	v_add_u32_e32 v81, 0, v197
	v_add_u32_e32 v90, 0, v196
	v_add_u32_e32 v82, v81, v165
	v_add_u32_e32 v86, v90, v165
	v_add_u32_e32 v81, v81, v80
	ds_read_b128 v[82:85], v82 offset:49152
	ds_read_b128 v[86:89], v86 offset:49152
	v_add_u32_e32 v90, v90, v80
	ds_read_b128 v[146:149], v81 offset:49152
	ds_read_b128 v[150:153], v90 offset:49152
	v_add_u32_e32 v81, 0, v195
	v_add_u32_e32 v90, v81, v165
	v_add_u32_e32 v91, 0, v194
	v_add_u32_e32 v81, v81, v80
	v_add_u32_e32 v92, v91, v165
	ds_read_b128 v[210:213], v90 offset:49152
	ds_read_b128 v[214:217], v92 offset:49152
	v_add_u32_e32 v80, v91, v80
	ds_read_b128 v[222:225], v81 offset:49152
	ds_read_b128 v[226:229], v80 offset:49152
	s_waitcnt lgkmcnt(6)
	v_mfma_f32_32x32x64_f8f6f4 v[96:111], v[82:89], v[122:129], 0
	s_waitcnt lgkmcnt(4)
	v_mfma_f32_32x32x64_f8f6f4 v[80:95], v[146:153], v[122:129], 0
	s_waitcnt lgkmcnt(2)
	v_mfma_f32_32x32x64_f8f6f4 v[96:111], v[210:217], v[130:137], v[96:111]
	s_waitcnt lgkmcnt(0)
	v_mfma_f32_32x32x64_f8f6f4 v[80:95], v[222:229], v[130:137], v[80:95]
	v_exp_f32_e32 v122, v170
	v_exp_f32_e32 v123, v171
	v_exp_f32_e32 v134, v158
	v_exp_f32_e32 v135, v159
	v_exp_f32_e32 v139, v154
	v_exp_f32_e32 v146, v155
	v_exp_f32_e32 v142, v142
	v_exp_f32_e32 v143, v143
	v_cvt_pk_fp8_f32 v124, v219, v220
	v_cvt_pk_fp8_f32 v125, v185, v218
	v_exp_f32_e32 v132, v160
	v_exp_f32_e32 v133, v161
	v_exp_f32_e32 v136, v156
	v_exp_f32_e32 v137, v157
	v_exp_f32_e32 v144, v144
	v_exp_f32_e32 v145, v145
	v_exp_f32_e32 v140, v140
	v_exp_f32_e32 v141, v141
	v_cvt_pk_fp8_f32 v128, v122, v123
	v_cvt_pk_fp8_f32 v129, v134, v135
	v_cvt_pk_fp8_f32 v124, v179, v181 op_sel:[0,0,1]
	v_cvt_pk_fp8_f32 v125, v183, v184 op_sel:[0,0,1]
	v_cvt_pk_fp8_f32 v126, v180, v182
	v_cvt_pk_fp8_f32 v130, v139, v146
	v_cvt_pk_fp8_f32 v127, v177, v178
	v_cvt_pk_fp8_f32 v131, v142, v143
	v_cvt_pk_fp8_f32 v128, v132, v133 op_sel:[0,0,1]
	v_cvt_pk_fp8_f32 v129, v136, v137 op_sel:[0,0,1]
	v_cvt_pk_fp8_f32 v126, v173, v174 op_sel:[0,0,1]
	v_cvt_pk_fp8_f32 v130, v144, v145 op_sel:[0,0,1]
	v_cvt_pk_fp8_f32 v127, v175, v176 op_sel:[0,0,1]
	v_cvt_pk_fp8_f32 v131, v140, v141 op_sel:[0,0,1]
	v_add_u32_e32 v123, 0, v162
	v_add_u32_e32 v122, v123, v199
	v_add_u32_e32 v123, v123, v200
	ds_read_b128 v[140:143], v122
	ds_read_b128 v[148:151], v122 offset:2048
	ds_read_b128 v[144:147], v123
	ds_read_b128 v[152:155], v123 offset:2048
	ds_read_b128 v[174:177], v122 offset:4096
	ds_read_b128 v[200:203], v122 offset:6144
	ds_read_b128 v[178:181], v123 offset:4096
	ds_read_b128 v[204:207], v123 offset:6144
	s_waitcnt lgkmcnt(5)
	s_nop 3
	v_mfma_f32_32x32x64_f8f6f4 v[48:63], v[124:131], v[140:147], v[48:63]
	s_waitcnt lgkmcnt(4)
	v_mfma_f32_32x32x64_f8f6f4 v[32:47], v[124:131], v[148:155], v[32:47]
	s_waitcnt lgkmcnt(1)
	v_mfma_f32_32x32x64_f8f6f4 v[16:31], v[124:131], v[174:181], v[16:31]
	s_waitcnt lgkmcnt(0)
	v_mfma_f32_32x32x64_f8f6f4 v[0:15], v[124:131], v[200:207], v[0:15]
	v_mfma_f32_16x16x128_f8f6f4 v[64:67], v[124:131], v[114:121], v[64:67]
	s_nop 15
	s_nop 7
	v_max_f32_e32 v124, v97, v97
	v_max_f32_e32 v125, v96, v96
	v_max_f32_e32 v124, v125, v124
	v_max3_f32 v124, v124, v98, v99
	v_max3_f32 v124, v124, v100, v101
	v_max3_f32 v124, v124, v102, v103
	v_max3_f32 v124, v124, v104, v105
	v_max3_f32 v124, v124, v106, v107
	v_max3_f32 v124, v124, v108, v109
	v_max3_f32 v124, v124, v110, v111
	v_max3_f32 v124, v124, v80, v81
	v_max3_f32 v124, v124, v82, v83
	v_max3_f32 v124, v124, v84, v85
	v_max3_f32 v124, v124, v86, v87
	v_max3_f32 v124, v124, v88, v89
	v_max3_f32 v124, v124, v90, v91
	v_max3_f32 v124, v124, v92, v93
	v_max3_f32 v124, v124, v94, v95
	v_mov_b32_e32 v125, v124
	s_nop 1
	v_permlane32_swap_b32_e32 v124, v125
	v_max_f32_e32 v125, v125, v125
	v_max_f32_e32 v124, v124, v124
	v_max_f32_e32 v125, v124, v125
	v_sub_f32_e32 v124, v125, v172
	v_cmp_ge_f32_e32 vcc, s63, v124
	s_cmp_lg_u64 vcc, exec
	s_cselect_b64 s[6:7], -1, 0
	s_mov_b64 s[4:5], -1
	s_mov_b64 vcc, s[6:7]
	s_cbranch_vccnz .LBB0_235
	s_andn2_b64 vcc, exec, s[4:5]
	s_cbranch_vccnz .LBB0_163

.LBB0_163:
	s_and_b64 vcc, exec, s[6:7]
	s_barrier
	s_cbranch_vccz .LBB0_167
	v_cmp_eq_u32_e32 vcc, 0, v193
	s_and_saveexec_b64 s[4:5], vcc
	v_lshl_add_u32 v125, v113, 2, v198
	ds_write_b32 v125, v124 offset:128
	s_or_b64 exec, exec, s[4:5]
	s_waitcnt lgkmcnt(0)
	v_lshl_add_u32 v136, v193, 4, v198
	ds_read_b128 v[124:127], v136 offset:224
	ds_read_b128 v[128:131], v136 offset:192
	ds_read_b128 v[132:135], v136 offset:160
	ds_read_b128 v[140:143], v136 offset:128
	s_waitcnt lgkmcnt(3)
	v_pk_mul_f32 v[62:63], v[62:63], v[126:127]
	s_waitcnt lgkmcnt(2)
	v_pk_mul_f32 v[58:59], v[58:59], v[130:131]
	s_waitcnt lgkmcnt(1)
	v_pk_mul_f32 v[54:55], v[54:55], v[134:135]
	s_waitcnt lgkmcnt(0)
	v_pk_mul_f32 v[50:51], v[50:51], v[142:143]
	v_pk_mul_f32 v[60:61], v[60:61], v[124:125]
	v_pk_mul_f32 v[56:57], v[56:57], v[128:129]
	v_pk_mul_f32 v[52:53], v[52:53], v[132:133]
	v_pk_mul_f32 v[48:49], v[48:49], v[140:141]
	v_pk_mul_f32 v[46:47], v[46:47], v[126:127]
	v_pk_mul_f32 v[42:43], v[42:43], v[130:131]
	v_pk_mul_f32 v[38:39], v[38:39], v[134:135]
	v_pk_mul_f32 v[34:35], v[34:35], v[142:143]
	v_pk_mul_f32 v[44:45], v[44:45], v[124:125]
	v_pk_mul_f32 v[40:41], v[40:41], v[128:129]
	v_pk_mul_f32 v[36:37], v[36:37], v[132:133]
	v_pk_mul_f32 v[32:33], v[32:33], v[140:141]
	v_pk_mul_f32 v[30:31], v[30:31], v[126:127]
	v_pk_mul_f32 v[26:27], v[26:27], v[130:131]
	v_pk_mul_f32 v[22:23], v[22:23], v[134:135]
	v_pk_mul_f32 v[18:19], v[18:19], v[142:143]
	v_pk_mul_f32 v[28:29], v[28:29], v[124:125]
	v_pk_mul_f32 v[24:25], v[24:25], v[128:129]
	v_pk_mul_f32 v[20:21], v[20:21], v[132:133]
	v_pk_mul_f32 v[16:17], v[16:17], v[140:141]
	v_pk_mul_f32 v[14:15], v[14:15], v[126:127]
	v_pk_mul_f32 v[10:11], v[10:11], v[130:131]
	v_pk_mul_f32 v[6:7], v[6:7], v[134:135]
	v_pk_mul_f32 v[2:3], v[2:3], v[142:143]
	v_pk_mul_f32 v[12:13], v[12:13], v[124:125]
	v_pk_mul_f32 v[8:9], v[8:9], v[128:129]
	v_pk_mul_f32 v[4:5], v[4:5], v[132:133]
	v_pk_mul_f32 v[0:1], v[0:1], v[140:141]
	v_mbcnt_lo_u32_b32 v136, -1, 0
	v_mbcnt_hi_u32_b32 v136, -1, v136
	v_and_b32_e32 v124, 8, v136
	v_and_b32_e32 v136, 0x30, v136
	v_lshl_add_u32 v136, v124, 3, v136
	v_add_u32_e32 v136, v136, v198
	ds_read_b128 v[124:127], v136 offset:128
	s_waitcnt lgkmcnt(0)
	v_pk_mul_f32 v[64:65], v[64:65], v[124:125]
	v_pk_mul_f32 v[66:67], v[66:67], v[126:127]
.LBB0_167:
	v_pk_fma_f32 v[96:97], v[96:97], s[62:63], v[138:139] op_sel_hi:[1,0,0]
	v_pk_fma_f32 v[80:81], v[80:81], s[62:63], v[138:139] op_sel_hi:[1,0,0]
	v_pk_fma_f32 v[98:99], v[98:99], s[62:63], v[138:139] op_sel_hi:[1,0,0]
	v_pk_fma_f32 v[100:101], v[100:101], s[62:63], v[138:139] op_sel_hi:[1,0,0]
	v_pk_fma_f32 v[84:85], v[84:85], s[62:63], v[138:139] op_sel_hi:[1,0,0]
	v_pk_fma_f32 v[126:127], v[104:105], s[62:63], v[138:139] op_sel_hi:[1,0,0]
	v_pk_fma_f32 v[88:89], v[88:89], s[62:63], v[138:139] op_sel_hi:[1,0,0]
	v_pk_fma_f32 v[128:129], v[106:107], s[62:63], v[138:139] op_sel_hi:[1,0,0]
	v_pk_fma_f32 v[92:93], v[92:93], s[62:63], v[138:139] op_sel_hi:[1,0,0]
	v_pk_fma_f32 v[132:133], v[110:111], s[62:63], v[138:139] op_sel_hi:[1,0,0]
	v_exp_f32_e32 v124, v96
	v_exp_f32_e32 v125, v97
	v_exp_f32_e32 v104, v98
	v_exp_f32_e32 v106, v99
	v_exp_f32_e32 v110, v100
	v_exp_f32_e32 v111, v101
	v_exp_f32_e32 v105, v126
	v_exp_f32_e32 v107, v127
	v_exp_f32_e32 v98, v128
	v_exp_f32_e32 v99, v129
	v_pk_fma_f32 v[96:97], v[90:91], s[62:63], v[138:139] op_sel_hi:[1,0,0]
	v_pk_fma_f32 v[90:91], v[94:95], s[62:63], v[138:139] op_sel_hi:[1,0,0]
	v_exp_f32_e32 v94, v80
	v_exp_f32_e32 v95, v81
	v_exp_f32_e32 v128, v84
	v_exp_f32_e32 v129, v85
	v_exp_f32_e32 v88, v88
	v_exp_f32_e32 v89, v89
	v_exp_f32_e32 v92, v92
	v_exp_f32_e32 v93, v93
	v_pk_fma_f32 v[82:83], v[82:83], s[62:63], v[138:139] op_sel_hi:[1,0,0]
	v_pk_fma_f32 v[102:103], v[102:103], s[62:63], v[138:139] op_sel_hi:[1,0,0]
	v_pk_fma_f32 v[86:87], v[86:87], s[62:63], v[138:139] op_sel_hi:[1,0,0]
	v_pk_fma_f32 v[130:131], v[108:109], s[62:63], v[138:139] op_sel_hi:[1,0,0]
	v_exp_f32_e32 v108, v102
	v_exp_f32_e32 v109, v103
	v_exp_f32_e32 v102, v130
	v_exp_f32_e32 v103, v131
	v_exp_f32_e32 v126, v82
	v_exp_f32_e32 v127, v83
	v_exp_f32_e32 v130, v86
	v_exp_f32_e32 v131, v87
	v_exp_f32_e32 v96, v96
	v_exp_f32_e32 v97, v97
	v_exp_f32_e32 v90, v90
	v_exp_f32_e32 v91, v91
	v_cvt_pk_fp8_f32 v80, v124, v125
	v_cvt_pk_fp8_f32 v84, v94, v95
	v_cvt_pk_fp8_f32 v81, v110, v111
	v_cvt_pk_fp8_f32 v85, v128, v129
	v_cvt_pk_fp8_f32 v82, v105, v107
	v_cvt_pk_fp8_f32 v86, v88, v89
	v_cvt_pk_fp8_f32 v87, v92, v93
	v_exp_f32_e32 v100, v132
	v_exp_f32_e32 v101, v133
	v_cvt_pk_fp8_f32 v80, v104, v106 op_sel:[0,0,1]
	v_cvt_pk_fp8_f32 v84, v126, v127 op_sel:[0,0,1]
	v_cvt_pk_fp8_f32 v81, v108, v109 op_sel:[0,0,1]
	v_cvt_pk_fp8_f32 v85, v130, v131 op_sel:[0,0,1]
	v_cvt_pk_fp8_f32 v83, v102, v103
	v_cvt_pk_fp8_f32 v82, v98, v99 op_sel:[0,0,1]
	v_cvt_pk_fp8_f32 v86, v96, v97 op_sel:[0,0,1]
	v_cvt_pk_fp8_f32 v87, v90, v91 op_sel:[0,0,1]
	v_cvt_pk_fp8_f32 v83, v100, v101 op_sel:[0,0,1]
	s_cmp_eq_u32 s60, 0
	ds_read_b128 v[88:91], v122 offset:16384
	ds_read_b128 v[96:99], v122 offset:18432
	ds_read_b128 v[92:95], v123 offset:16384
	ds_read_b128 v[100:103], v123 offset:18432
	ds_read_b128 v[104:107], v122 offset:20480
	ds_read_b128 v[124:127], v122 offset:22528
	ds_read_b128 v[108:111], v123 offset:20480
	ds_read_b128 v[128:131], v123 offset:22528
	v_ashrrev_i32_e32 v165, 31, v164
	s_waitcnt lgkmcnt(5)
	s_nop 3
	v_mfma_f32_32x32x64_f8f6f4 v[48:63], v[80:87], v[88:95], v[48:63]
	s_waitcnt lgkmcnt(4)
	v_mfma_f32_32x32x64_f8f6f4 v[32:47], v[80:87], v[96:103], v[32:47]
	s_waitcnt lgkmcnt(1)
	v_mfma_f32_32x32x64_f8f6f4 v[16:31], v[80:87], v[104:111], v[16:31]
	s_waitcnt lgkmcnt(0)
	v_mfma_f32_32x32x64_f8f6f4 v[0:15], v[80:87], v[124:131], v[0:15]
	v_mfma_f32_16x16x128_f8f6f4 v[64:67], v[80:87], v[114:121], v[64:67]
	s_nop 15
	s_nop 7
	v_lshlrev_b32_e32 v80, 3, v164
	v_lshlrev_b32_e32 v81, 5, v193
	v_and_b32_e32 v82, 16, v113
	v_add_u32_e32 v81, v81, v82
	v_and_b32_e32 v82, 8, v113
	v_lshl_add_u32 v81, v82, 3, v81
	v_add_u32_e32 v81, v81, v80
	v_add_u32_e32 v81, 0x10000, v81
	v_and_b32_e32 v82, 7, v113
	v_cmp_eq_u32_e32 vcc, 0, v82
	s_and_saveexec_b64 s[4:5], vcc
	ds_write_b128 v81, v[64:67]
	s_or_b64 exec, exec, s[4:5]
	v_lshl_add_u32 v80, v193, 4, v80
	v_add_u32_e32 v80, 0x10000, v80
	s_waitcnt lgkmcnt(0)
	ds_read_b128 v[64:67], v80
	ds_read_b128 v[68:71], v80 offset:32
	ds_read_b128 v[72:75], v80 offset:64
	ds_read_b128 v[76:79], v80 offset:96
	s_waitcnt lgkmcnt(0)
	s_cmp_eq_u32 s60, 0
	s_cbranch_scc1 .Lepi8_d
